# grid barrier: non-leader workgroups poll the global generation word directly instead of the per-XCD word bumped by their XCD leader (one global round trip less per seam, 12 seams)
# speedup vs baseline: 1.0027x; 1.0027x over previous
; __device__ __forceinline__ unsigned xb_ld(unsigned* p)              { return __hip_atomic_load(p, __ATOMIC_RELAXED, __HIP_MEMORY_SCOPE_AGENT); }
; __device__ __forceinline__ unsigned xb_add(unsigned* p, unsigned v) { return __hip_atomic_fetch_add(p, v, __ATOMIC_RELAXED, __HIP_MEMORY_SCOPE_AGENT); }
; #define XB_SPIN(cond, bar) do { unsigned _sp = 0; while (cond) { __builtin_amdgcn_s_sleep(1); \
;     if ((++_sp & 255u) == 0u) { if (xb_ld(&(bar)[XB_TMO])) break; if (_sp > XB_SPIN_CAP) { atomicAdd(&(bar)[XB_TMO], 1u); break; } } } } while (0)
; __device__ __forceinline__ void xcd_barrier(const XcdBarrier& b) {
;     ...
;         const unsigned old = xb_add(&bar[XB_XSUB(b.x)], 1u);
;         const unsigned gen = old / nloc;
;         if (old + 1u == (gen + 1u) * nloc) {
;             __builtin_amdgcn_fence(__ATOMIC_RELEASE, "agent");
;             asm volatile("s_waitcnt vmcnt(0)" ::: "memory");
;             const unsigned og = xb_add(&bar[XB_TOP], 1u);
;             const unsigned tg = og / nx;
;             if (og + 1u == (tg + 1u) * nx) xb_add(&bar[XB_TOPGEN], 1u);
;             else XB_SPIN(xb_ld(&bar[XB_TOPGEN]) == tg, bar);
;             __builtin_amdgcn_fence(__ATOMIC_ACQUIRE, "agent");
;             xb_add(&bar[XB_XGEN(b.x)], 1u);
;             asm volatile("s_waitcnt vmcnt(0)" ::: "memory");
;         } else {
;             XB_SPIN(xb_ld(&bar[XB_XGEN(b.x)]) == gen, bar);
;             __builtin_amdgcn_fence(__ATOMIC_ACQUIRE, "agent");
;             asm volatile("s_waitcnt vmcnt(0)" ::: "memory");
.LBB0_250:
	s_lshl_b32 s4, s74, 8
	s_add_u32 s4, s72, s4
	s_addc_u32 s5, s73, 0
	v_mov_b32_e32 v1, 0x1000
	v_mov_b32_e32 v3, 1
	global_atomic_add v3, v1, v3, s[4:5] offset:1024 sc0
	v_cvt_f32_u32_e32 v1, v2
	v_sub_u32_e32 v4, 0, v2
	v_rcp_iflag_f32_e32 v1, v1
	s_nop 0
	v_mul_f32_e32 v1, 0x4f7ffffe, v1
	v_cvt_u32_f32_e32 v1, v1
	v_mul_lo_u32 v4, v4, v1
	v_mul_hi_u32 v4, v1, v4
	v_add_u32_e32 v1, v1, v4
	s_waitcnt vmcnt(0)
	v_mul_hi_u32 v1, v3, v1
	v_mul_lo_u32 v4, v1, v2
	v_sub_u32_e32 v4, v3, v4
	v_add_u32_e32 v5, 1, v1
	v_cmp_ge_u32_e32 vcc, v4, v2
	v_add_u32_e32 v3, 1, v3
	s_nop 0
	v_cndmask_b32_e32 v1, v1, v5, vcc
	v_sub_u32_e32 v5, v4, v2
	v_cndmask_b32_e32 v4, v4, v5, vcc
	v_add_u32_e32 v5, 1, v1
	v_cmp_ge_u32_e32 vcc, v4, v2
	s_nop 1
	v_cndmask_b32_e32 v1, v1, v5, vcc
	v_mul_lo_u32 v4, v2, v1
	v_add_u32_e32 v2, v4, v2
	v_cmp_ne_u32_e32 vcc, v3, v2
	s_and_saveexec_b64 s[10:11], vcc
	s_xor_b64 s[10:11], exec, s[10:11]
	s_cbranch_execz .LBB0_264
	s_waitcnt lgkmcnt(0)
	s_add_u32 s16, s72, 0x3500
	s_addc_u32 s17, s73, 0
	v_mov_b32_e32 v0, 0
	global_load_dword v0, v0, s[16:17] sc1
	s_waitcnt vmcnt(0)
	v_cmp_eq_u32_e32 vcc, v0, v1
	s_and_saveexec_b64 s[12:13], vcc
	s_cbranch_execz .LBB0_263
	s_add_u32 s14, s64, 0x2aa4200
	s_addc_u32 s15, s65, 0
	s_mov_b32 s28, 1
	s_mov_b64 s[18:19], 0
	v_mov_b32_e32 v0, 0
	s_branch .LBB0_254

; __device__ __forceinline__ unsigned xb_ld(unsigned* p)              { return __hip_atomic_load(p, __ATOMIC_RELAXED, __HIP_MEMORY_SCOPE_AGENT); }
; __device__ __forceinline__ unsigned xb_add(unsigned* p, unsigned v) { return __hip_atomic_fetch_add(p, v, __ATOMIC_RELAXED, __HIP_MEMORY_SCOPE_AGENT); }
; #define XB_SPIN(cond, bar) do { unsigned _sp = 0; while (cond) { __builtin_amdgcn_s_sleep(1); \
;     if ((++_sp & 255u) == 0u) { if (xb_ld(&(bar)[XB_TMO])) break; if (_sp > XB_SPIN_CAP) { atomicAdd(&(bar)[XB_TMO], 1u); break; } } } } while (0)
; __device__ __forceinline__ void xcd_barrier(const XcdBarrier& b) {
;     ...
;         const unsigned old = xb_add(&bar[XB_XSUB(b.x)], 1u);
;         const unsigned gen = old / nloc;
;         if (old + 1u == (gen + 1u) * nloc) {
;             __builtin_amdgcn_fence(__ATOMIC_RELEASE, "agent");
;             asm volatile("s_waitcnt vmcnt(0)" ::: "memory");
;             const unsigned og = xb_add(&bar[XB_TOP], 1u);
;             const unsigned tg = og / nx;
;             if (og + 1u == (tg + 1u) * nx) xb_add(&bar[XB_TOPGEN], 1u);
;             else XB_SPIN(xb_ld(&bar[XB_TOPGEN]) == tg, bar);
;             __builtin_amdgcn_fence(__ATOMIC_ACQUIRE, "agent");
;             xb_add(&bar[XB_XGEN(b.x)], 1u);
;             asm volatile("s_waitcnt vmcnt(0)" ::: "memory");
;         } else {
;             XB_SPIN(xb_ld(&bar[XB_XGEN(b.x)]) == gen, bar);
;             __builtin_amdgcn_fence(__ATOMIC_ACQUIRE, "agent");
;             asm volatile("s_waitcnt vmcnt(0)" ::: "memory");
.LBB0_410:
	s_lshl_b32 s4, s74, 8
	s_add_u32 s4, s72, s4
	s_addc_u32 s5, s73, 0
	v_mov_b32_e32 v1, 0x1000
	v_mov_b32_e32 v3, 1
	global_atomic_add v3, v1, v3, s[4:5] offset:1024 sc0
	v_cvt_f32_u32_e32 v1, v2
	v_sub_u32_e32 v4, 0, v2
	v_rcp_iflag_f32_e32 v1, v1
	s_nop 0
	v_mul_f32_e32 v1, 0x4f7ffffe, v1
	v_cvt_u32_f32_e32 v1, v1
	v_mul_lo_u32 v4, v4, v1
	v_mul_hi_u32 v4, v1, v4
	v_add_u32_e32 v1, v1, v4
	s_waitcnt vmcnt(0)
	v_mul_hi_u32 v1, v3, v1
	v_mul_lo_u32 v4, v1, v2
	v_sub_u32_e32 v4, v3, v4
	v_add_u32_e32 v5, 1, v1
	v_cmp_ge_u32_e32 vcc, v4, v2
	v_add_u32_e32 v3, 1, v3
	s_nop 0
	v_cndmask_b32_e32 v1, v1, v5, vcc
	v_sub_u32_e32 v5, v4, v2
	v_cndmask_b32_e32 v4, v4, v5, vcc
	v_add_u32_e32 v5, 1, v1
	v_cmp_ge_u32_e32 vcc, v4, v2
	s_nop 1
	v_cndmask_b32_e32 v1, v1, v5, vcc
	v_mul_lo_u32 v4, v2, v1
	v_add_u32_e32 v2, v4, v2
	v_cmp_ne_u32_e32 vcc, v3, v2
	s_and_saveexec_b64 s[8:9], vcc
	s_xor_b64 s[8:9], exec, s[8:9]
	s_cbranch_execz .LBB0_424
	s_waitcnt lgkmcnt(0)
	s_add_u32 s14, s72, 0x3500
	s_addc_u32 s15, s73, 0
	v_mov_b32_e32 v0, 0
	global_load_dword v0, v0, s[14:15] sc1
	s_waitcnt vmcnt(0)
	v_cmp_eq_u32_e32 vcc, v0, v1
	s_and_saveexec_b64 s[10:11], vcc
	s_cbranch_execz .LBB0_423
	s_add_u32 s12, s64, 0x2aa4200
	s_addc_u32 s13, s65, 0
	s_mov_b32 s26, 1
	s_mov_b64 s[16:17], 0
	v_mov_b32_e32 v0, 0
	s_branch .LBB0_414

; __device__ __forceinline__ unsigned xb_ld(unsigned* p)              { return __hip_atomic_load(p, __ATOMIC_RELAXED, __HIP_MEMORY_SCOPE_AGENT); }
; __device__ __forceinline__ unsigned xb_add(unsigned* p, unsigned v) { return __hip_atomic_fetch_add(p, v, __ATOMIC_RELAXED, __HIP_MEMORY_SCOPE_AGENT); }
; #define XB_SPIN(cond, bar) do { unsigned _sp = 0; while (cond) { __builtin_amdgcn_s_sleep(1); \
;     if ((++_sp & 255u) == 0u) { if (xb_ld(&(bar)[XB_TMO])) break; if (_sp > XB_SPIN_CAP) { atomicAdd(&(bar)[XB_TMO], 1u); break; } } } } while (0)
; __device__ __forceinline__ void xcd_barrier(const XcdBarrier& b) {
;     ...
;         const unsigned old = xb_add(&bar[XB_XSUB(b.x)], 1u);
;         const unsigned gen = old / nloc;
;         if (old + 1u == (gen + 1u) * nloc) {
;             __builtin_amdgcn_fence(__ATOMIC_RELEASE, "agent");
;             asm volatile("s_waitcnt vmcnt(0)" ::: "memory");
;             const unsigned og = xb_add(&bar[XB_TOP], 1u);
;             const unsigned tg = og / nx;
;             if (og + 1u == (tg + 1u) * nx) xb_add(&bar[XB_TOPGEN], 1u);
;             else XB_SPIN(xb_ld(&bar[XB_TOPGEN]) == tg, bar);
;             __builtin_amdgcn_fence(__ATOMIC_ACQUIRE, "agent");
;             xb_add(&bar[XB_XGEN(b.x)], 1u);
;             asm volatile("s_waitcnt vmcnt(0)" ::: "memory");
;         } else {
;             XB_SPIN(xb_ld(&bar[XB_XGEN(b.x)]) == gen, bar);
;             __builtin_amdgcn_fence(__ATOMIC_ACQUIRE, "agent");
;             asm volatile("s_waitcnt vmcnt(0)" ::: "memory");
.LBB0_480:
	s_lshl_b32 s8, s74, 8
	s_add_u32 s8, s72, s8
	s_addc_u32 s9, s73, 0
	v_mov_b32_e32 v1, 0x1000
	v_mov_b32_e32 v3, 1
	global_atomic_add v3, v1, v3, s[8:9] offset:1024 sc0
	v_cvt_f32_u32_e32 v1, v2
	v_sub_u32_e32 v4, 0, v2
	v_rcp_iflag_f32_e32 v1, v1
	s_nop 0
	v_mul_f32_e32 v1, 0x4f7ffffe, v1
	v_cvt_u32_f32_e32 v1, v1
	v_mul_lo_u32 v4, v4, v1
	v_mul_hi_u32 v4, v1, v4
	v_add_u32_e32 v1, v1, v4
	s_waitcnt vmcnt(0)
	v_mul_hi_u32 v1, v3, v1
	v_mul_lo_u32 v4, v1, v2
	v_sub_u32_e32 v4, v3, v4
	v_add_u32_e32 v5, 1, v1
	v_cmp_ge_u32_e32 vcc, v4, v2
	v_add_u32_e32 v3, 1, v3
	s_nop 0
	v_cndmask_b32_e32 v1, v1, v5, vcc
	v_sub_u32_e32 v5, v4, v2
	v_cndmask_b32_e32 v4, v4, v5, vcc
	v_add_u32_e32 v5, 1, v1
	v_cmp_ge_u32_e32 vcc, v4, v2
	s_nop 1
	v_cndmask_b32_e32 v1, v1, v5, vcc
	v_mul_lo_u32 v4, v2, v1
	v_add_u32_e32 v2, v4, v2
	v_cmp_ne_u32_e32 vcc, v3, v2
	s_and_saveexec_b64 s[10:11], vcc
	s_xor_b64 s[10:11], exec, s[10:11]
	s_cbranch_execz .LBB0_494
	s_waitcnt lgkmcnt(0)
	s_add_u32 s16, s72, 0x3500
	s_addc_u32 s17, s73, 0
	v_mov_b32_e32 v0, 0
	global_load_dword v0, v0, s[16:17] sc1
	s_waitcnt vmcnt(0)
	v_cmp_eq_u32_e32 vcc, v0, v1
	s_and_saveexec_b64 s[12:13], vcc
	s_cbranch_execz .LBB0_493
	s_add_u32 s14, s64, 0x2aa4200
	s_addc_u32 s15, s65, 0
	s_mov_b32 s28, 1
	s_mov_b64 s[18:19], 0
	v_mov_b32_e32 v0, 0
	s_branch .LBB0_484

; __device__ __forceinline__ unsigned xb_ld(unsigned* p)              { return __hip_atomic_load(p, __ATOMIC_RELAXED, __HIP_MEMORY_SCOPE_AGENT); }
; __device__ __forceinline__ unsigned xb_add(unsigned* p, unsigned v) { return __hip_atomic_fetch_add(p, v, __ATOMIC_RELAXED, __HIP_MEMORY_SCOPE_AGENT); }
; #define XB_SPIN(cond, bar) do { unsigned _sp = 0; while (cond) { __builtin_amdgcn_s_sleep(1); \
;     if ((++_sp & 255u) == 0u) { if (xb_ld(&(bar)[XB_TMO])) break; if (_sp > XB_SPIN_CAP) { atomicAdd(&(bar)[XB_TMO], 1u); break; } } } } while (0)
; __device__ __forceinline__ void xcd_barrier(const XcdBarrier& b) {
;     ...
;         const unsigned old = xb_add(&bar[XB_XSUB(b.x)], 1u);
;         const unsigned gen = old / nloc;
;         if (old + 1u == (gen + 1u) * nloc) {
;             __builtin_amdgcn_fence(__ATOMIC_RELEASE, "agent");
;             asm volatile("s_waitcnt vmcnt(0)" ::: "memory");
;             const unsigned og = xb_add(&bar[XB_TOP], 1u);
;             const unsigned tg = og / nx;
;             if (og + 1u == (tg + 1u) * nx) xb_add(&bar[XB_TOPGEN], 1u);
;             else XB_SPIN(xb_ld(&bar[XB_TOPGEN]) == tg, bar);
;             __builtin_amdgcn_fence(__ATOMIC_ACQUIRE, "agent");
;             xb_add(&bar[XB_XGEN(b.x)], 1u);
;             asm volatile("s_waitcnt vmcnt(0)" ::: "memory");
;         } else {
;             XB_SPIN(xb_ld(&bar[XB_XGEN(b.x)]) == gen, bar);
;             __builtin_amdgcn_fence(__ATOMIC_ACQUIRE, "agent");
;             asm volatile("s_waitcnt vmcnt(0)" ::: "memory");
.LBB0_581:
	s_lshl_b32 s4, s74, 8
	s_add_u32 s4, s72, s4
	s_addc_u32 s5, s73, 0
	v_mov_b32_e32 v1, 0x1000
	v_mov_b32_e32 v3, 1
	global_atomic_add v3, v1, v3, s[4:5] offset:1024 sc0
	v_cvt_f32_u32_e32 v1, v2
	v_sub_u32_e32 v4, 0, v2
	v_rcp_iflag_f32_e32 v1, v1
	s_nop 0
	v_mul_f32_e32 v1, 0x4f7ffffe, v1
	v_cvt_u32_f32_e32 v1, v1
	v_mul_lo_u32 v4, v4, v1
	v_mul_hi_u32 v4, v1, v4
	v_add_u32_e32 v1, v1, v4
	s_waitcnt vmcnt(0)
	v_mul_hi_u32 v1, v3, v1
	v_mul_lo_u32 v4, v1, v2
	v_sub_u32_e32 v4, v3, v4
	v_add_u32_e32 v5, 1, v1
	v_cmp_ge_u32_e32 vcc, v4, v2
	v_add_u32_e32 v3, 1, v3
	s_nop 0
	v_cndmask_b32_e32 v1, v1, v5, vcc
	v_sub_u32_e32 v5, v4, v2
	v_cndmask_b32_e32 v4, v4, v5, vcc
	v_add_u32_e32 v5, 1, v1
	v_cmp_ge_u32_e32 vcc, v4, v2
	s_nop 1
	v_cndmask_b32_e32 v1, v1, v5, vcc
	v_mul_lo_u32 v4, v2, v1
	v_add_u32_e32 v2, v4, v2
	v_cmp_ne_u32_e32 vcc, v3, v2
	s_and_saveexec_b64 s[6:7], vcc
	s_xor_b64 s[6:7], exec, s[6:7]
	s_cbranch_execz .LBB0_595
	s_waitcnt lgkmcnt(0)
	s_add_u32 s12, s72, 0x3500
	s_addc_u32 s13, s73, 0
	v_mov_b32_e32 v0, 0
	global_load_dword v0, v0, s[12:13] sc1
	s_waitcnt vmcnt(0)
	v_cmp_eq_u32_e32 vcc, v0, v1
	s_and_saveexec_b64 s[8:9], vcc
	s_cbranch_execz .LBB0_594
	s_add_u32 s10, s64, 0x2aa4200
	s_addc_u32 s11, s65, 0
	s_mov_b32 s24, 1
	s_mov_b64 s[14:15], 0
	v_mov_b32_e32 v0, 0
	s_branch .LBB0_585

; __device__ __forceinline__ unsigned xb_ld(unsigned* p)              { return __hip_atomic_load(p, __ATOMIC_RELAXED, __HIP_MEMORY_SCOPE_AGENT); }
; __device__ __forceinline__ unsigned xb_add(unsigned* p, unsigned v) { return __hip_atomic_fetch_add(p, v, __ATOMIC_RELAXED, __HIP_MEMORY_SCOPE_AGENT); }
; #define XB_SPIN(cond, bar) do { unsigned _sp = 0; while (cond) { __builtin_amdgcn_s_sleep(1); \
;     if ((++_sp & 255u) == 0u) { if (xb_ld(&(bar)[XB_TMO])) break; if (_sp > XB_SPIN_CAP) { atomicAdd(&(bar)[XB_TMO], 1u); break; } } } } while (0)
; __device__ __forceinline__ void xcd_barrier(const XcdBarrier& b) {
;     ...
;         const unsigned old = xb_add(&bar[XB_XSUB(b.x)], 1u);
;         const unsigned gen = old / nloc;
;         if (old + 1u == (gen + 1u) * nloc) {
;             __builtin_amdgcn_fence(__ATOMIC_RELEASE, "agent");
;             asm volatile("s_waitcnt vmcnt(0)" ::: "memory");
;             const unsigned og = xb_add(&bar[XB_TOP], 1u);
;             const unsigned tg = og / nx;
;             if (og + 1u == (tg + 1u) * nx) xb_add(&bar[XB_TOPGEN], 1u);
;             else XB_SPIN(xb_ld(&bar[XB_TOPGEN]) == tg, bar);
;             __builtin_amdgcn_fence(__ATOMIC_ACQUIRE, "agent");
;             xb_add(&bar[XB_XGEN(b.x)], 1u);
;             asm volatile("s_waitcnt vmcnt(0)" ::: "memory");
;         } else {
;             XB_SPIN(xb_ld(&bar[XB_XGEN(b.x)]) == gen, bar);
;             __builtin_amdgcn_fence(__ATOMIC_ACQUIRE, "agent");
;             asm volatile("s_waitcnt vmcnt(0)" ::: "memory");
.LBB0_1101:
	s_lshl_b32 s6, s74, 8
	s_add_u32 s6, s72, s6
	s_addc_u32 s7, s73, 0
	v_mov_b32_e32 v1, 0x1000
	v_mov_b32_e32 v3, 1
	global_atomic_add v3, v1, v3, s[6:7] offset:1024 sc0
	v_cvt_f32_u32_e32 v1, v2
	v_sub_u32_e32 v4, 0, v2
	v_rcp_iflag_f32_e32 v1, v1
	s_nop 0
	v_mul_f32_e32 v1, 0x4f7ffffe, v1
	v_cvt_u32_f32_e32 v1, v1
	v_mul_lo_u32 v4, v4, v1
	v_mul_hi_u32 v4, v1, v4
	v_add_u32_e32 v1, v1, v4
	s_waitcnt vmcnt(0)
	v_mul_hi_u32 v1, v3, v1
	v_mul_lo_u32 v4, v1, v2
	v_sub_u32_e32 v4, v3, v4
	v_add_u32_e32 v5, 1, v1
	v_cmp_ge_u32_e32 vcc, v4, v2
	v_add_u32_e32 v3, 1, v3
	s_nop 0
	v_cndmask_b32_e32 v1, v1, v5, vcc
	v_sub_u32_e32 v5, v4, v2
	v_cndmask_b32_e32 v4, v4, v5, vcc
	v_add_u32_e32 v5, 1, v1
	v_cmp_ge_u32_e32 vcc, v4, v2
	s_nop 1
	v_cndmask_b32_e32 v1, v1, v5, vcc
	v_mul_lo_u32 v4, v2, v1
	v_add_u32_e32 v2, v4, v2
	v_cmp_ne_u32_e32 vcc, v3, v2
	s_and_saveexec_b64 s[8:9], vcc
	s_xor_b64 s[8:9], exec, s[8:9]
	s_cbranch_execz .LBB0_1115
	s_waitcnt lgkmcnt(0)
	s_add_u32 s14, s72, 0x3500
	s_addc_u32 s15, s73, 0
	v_mov_b32_e32 v0, 0
	global_load_dword v0, v0, s[14:15] sc1
	s_waitcnt vmcnt(0)
	v_cmp_eq_u32_e32 vcc, v0, v1
	s_and_saveexec_b64 s[10:11], vcc
	s_cbranch_execz .LBB0_1114
	s_add_u32 s12, s64, 0x2aa4200
	s_addc_u32 s13, s65, 0
	s_mov_b32 s26, 1
	s_mov_b64 s[16:17], 0
	v_mov_b32_e32 v0, 0
	s_branch .LBB0_1105
